# sub 4: half the workgroups (odd bx>>3) run attention before their mixer items, so mixer and attention work overlap across each XCD
# speedup vs baseline: 1.0007x; 1.0007x over previous
; #define LAS __attribute__((address_space(3)))
; __device__ __forceinline__ int ltid() { int t = threadIdx.x; asm volatile("" : "+v"(t)); return t; }
; __device__ __forceinline__ void mlstm_out(const Bufs& B, const float* __restrict__ g_out, int item, LAS unsigned char* lds) {
;     const int tid = ltid(), wid = tid >> 6, lane = tid & 63, wr = wid >> 2, wc = wid & 3, fr = lane & 15, fq = lane >> 4;
;     const int c = item >> 2, h = item & 3, s0 = c * 128;
;     constexpr float SC = 0.08838834764831845f;
;     LAS bf16_t* T0 = (LAS bf16_t*)(lds + CB0); LAS bf16_t* T1 = (LAS bf16_t*)(lds + CB1); LAS bf16_t* T2 = (LAS bf16_t*)(lds + CB2); LAS bf16_t* T3 = (LAS bf16_t*)(lds + CB3);
;     LAS float* vea = (LAS float*)(lds + CVEC); LAS float* veM = vea + 256; LAS float* vedn = vea + 512; LAS float* vn = vea + 768; LAS float* vqn = vea + 1024;
;     LAS float* vrs = vea + 1280; LAS float* vf = vea + 1408; LAS float* vsc = vea + 1536;
;     LAS float* HT = (LAS float*)(lds + CB1);
;     const float mst0 = B.MST[(0 * 4 + h) * 64 + c], mst1 = B.MST[(1 * 4 + h) * 64 + c];
; __global__ void __launch_bounds__(512) mega_fwd(Params p) {
;     ...
;         case 4: {
;             for (int it = bx; it < 256; it += G) mlstm_out(B, p.g_ml_out + l * 512, it, lds);
;             for (int it = bx; it < 256; it += G) ret_out(B, p.g_ret_out + l * 512, it, lds);
.LBB0_221:
	s_and_b64 vcc, exec, s[0:1]
	s_cbranch_vccz .LBB0_297
	v_readlane_b32 s0, v254, 3
	s_cmpk_gt_i32 s0, 0xff
	s_cbranch_scc1 .LBB0_297
	v_readlane_b32 s0, v254, 3
	s_bitcmp1_b32 s0, 3
	s_cselect_b32 s1, 1, 0
	v_writelane_b32 v255, s1, 62
	s_cbranch_scc1 .Lsub4_attn_first
.Lsub4_mixers:
	v_readlane_b32 s0, v254, 10
	s_lshl_b32 s0, s0, 9
	s_ashr_i32 s1, s0, 31
	s_lshl_b64 s[16:17], s[0:1], 2
	v_readlane_b32 s0, v253, 2
	v_readlane_b32 s12, v253, 14
	s_add_u32 s0, s12, s16
	v_writelane_b32 v254, s0, 44
	v_readlane_b32 s13, v253, 15
	v_writelane_b32 v254, s16, 46
	s_addc_u32 s0, s13, s17
	v_readlane_b32 s1, v253, 3
	v_writelane_b32 v254, s17, 47
	v_writelane_b32 v254, s0, 48
	v_readlane_b32 s5, v253, 7
	v_readlane_b32 s16, v254, 23
	v_readlane_b32 s0, v254, 4
	s_movk_i32 s5, 0x2400
	v_readlane_b32 s17, v254, 24
	v_readlane_b32 s2, v253, 4
	v_readlane_b32 s3, v253, 5
	v_readlane_b32 s4, v253, 6
	v_readlane_b32 s6, v253, 8
	v_readlane_b32 s7, v253, 9
	v_readlane_b32 s8, v253, 10
	v_readlane_b32 s9, v253, 11
	v_readlane_b32 s10, v253, 12
	v_readlane_b32 s11, v253, 13
	v_readlane_b32 s14, v253, 16
	v_readlane_b32 s15, v253, 17
	v_readlane_b32 s1, v254, 5

; #define LAS __attribute__((address_space(3)))
; __device__ __forceinline__ void ret_out(const Bufs& B, const float* __restrict__ g_out, int item, LAS unsigned char* lds) {
;     ...
;         mma_tile<64, 2>(accR, QB, 72, RT, 72, wr, wc, fr, fq);
; #pragma unroll
;         for (int m = 0; m < 4; ++m)
; #pragma unroll
;             for (int n = 0; n < 2; ++n) accR[m][n] *= gam;
;         mma_tile<128, 2>(accR, ST, 136, VT, 136, wr, wc, fr, fq);
;         __syncthreads();
; #pragma unroll
;         for (int m = 0; m < 4; ++m) { const f32x4 r4 = *(const LAS f32x4*)(vrw + dir * 128 + 64 * wr + 16 * m + 4 * fq);
; #pragma unroll
;             for (int n = 0; n < 2; ++n) yacc[m][n] += accR[m][n] * r4; }
;     }
;     const int erow = tid >> 2, eqd = tid & 3, es = s0 + erow;
;     u32x4 og4[4]; f32x4 gp4[8];
;     { const bf16_t* gg = B.PROJ + (size_t)es * NPROJP + PC_RG + h * 128 + eqd * 32; const float* gp = g_out + h * 128 + eqd * 32;
; #pragma unroll
;         for (int i = 0; i < 4; ++i) og4[i] = *(const u32x4*)(gg + i * 8);
; #pragma unroll
;         for (int i = 0; i < 8; ++i) gp4[i] = *(const f32x4*)(gp + i * 4); }
; #pragma unroll
;     for (int m = 0; m < 4; ++m)
; #pragma unroll
;         for (int n = 0; n < 2; ++n)
; #pragma unroll
;             for (int j = 0; j < 4; ++j) HT[(64 * wr + 16 * m + 4 * fq + j) * 132 + 32 * wc + 16 * n + fr] = yacc[m][n][j];
.LBB0_255:
	ds_read_b128 v[122:125], v121
	v_add_u32_e32 v126, 0xffffef00, v120
	ds_read_b128 v[126:129], v126
	ds_read_b128 v[130:133], v120
	s_add_i32 s30, s30, 32
	s_cmpk_lt_u32 s30, 0x60
	v_add_u32_e32 v120, 64, v120
	s_waitcnt lgkmcnt(1)
	v_mfma_f32_16x16x32_bf16 v[68:71], v[122:125], v[126:129], v[68:71]
	s_waitcnt lgkmcnt(0)
	v_mfma_f32_16x16x32_bf16 v[64:67], v[122:125], v[130:133], v[64:67]
	ds_read_b128 v[122:125], v121 offset:4352
	s_waitcnt lgkmcnt(0)
	v_mfma_f32_16x16x32_bf16 v[60:63], v[122:125], v[126:129], v[60:63]
	v_mfma_f32_16x16x32_bf16 v[56:59], v[122:125], v[130:133], v[56:59]
	ds_read_b128 v[122:125], v121 offset:8704
	s_waitcnt lgkmcnt(0)
	v_mfma_f32_16x16x32_bf16 v[52:55], v[122:125], v[126:129], v[52:55]
	v_mfma_f32_16x16x32_bf16 v[48:51], v[122:125], v[130:133], v[48:51]
	ds_read_b128 v[122:125], v121 offset:13056
	v_add_u32_e32 v121, 64, v121
	s_waitcnt lgkmcnt(0)
	v_mfma_f32_16x16x32_bf16 v[44:47], v[122:125], v[126:129], v[44:47]
	v_mfma_f32_16x16x32_bf16 v[40:43], v[122:125], v[130:133], v[40:43]
	s_cbranch_scc1 .LBB0_255
	v_add_u32_e32 v128, s33, v115
	s_barrier
	ds_read_b128 v[120:123], v128
	ds_read_b128 v[124:127], v128 offset:64
	s_movk_i32 s33, 0x200
	s_mov_b64 s[34:35], -1
	s_andn2_b64 vcc, exec, s[2:3]
	s_waitcnt lgkmcnt(1)
	v_pk_fma_f32 v[92:93], v[64:65], v[120:121], v[92:93]
	s_waitcnt lgkmcnt(0)
	v_pk_fma_f32 v[78:79], v[62:63], v[126:127], v[78:79]
	ds_read_b128 v[62:65], v128 offset:128
	v_pk_fma_f32 v[94:95], v[58:59], v[126:127], v[94:95]
	v_pk_fma_f32 v[98:99], v[56:57], v[124:125], v[98:99]
	ds_read_b128 v[56:59], v128 offset:192
	v_pk_fma_f32 v[76:77], v[70:71], v[122:123], v[76:77]
	v_pk_fma_f32 v[74:75], v[68:69], v[120:121], v[74:75]
	v_pk_fma_f32 v[88:89], v[66:67], v[122:123], v[88:89]
	v_pk_fma_f32 v[82:83], v[60:61], v[124:125], v[82:83]
	s_waitcnt lgkmcnt(1)
	v_pk_fma_f32 v[80:81], v[54:55], v[64:65], v[80:81]
	v_pk_fma_f32 v[86:87], v[52:53], v[62:63], v[86:87]
	v_pk_fma_f32 v[96:97], v[50:51], v[64:65], v[96:97]
	v_pk_fma_f32 v[102:103], v[48:49], v[62:63], v[102:103]
	s_waitcnt lgkmcnt(0)
	v_pk_fma_f32 v[84:85], v[46:47], v[58:59], v[84:85]
	v_pk_fma_f32 v[90:91], v[44:45], v[56:57], v[90:91]
	v_pk_fma_f32 v[100:101], v[42:43], v[58:59], v[100:101]
	v_pk_fma_f32 v[104:105], v[40:41], v[56:57], v[104:105]
	s_mov_b64 s[30:31], 0
	s_cbranch_vccnz .LBB0_250
	v_readlane_b32 s16, v254, 23
	v_readlane_b32 s0, v254, 44
	v_readlane_b32 s17, v254, 24
	v_readlane_b32 s1, v254, 45
	v_add_u32_e32 v64, s0, v109
	v_mov_b64_e32 v[0:1], s[16:17]
	s_movk_i32 s0, 0x2400
	v_mad_i64_i32 v[0:1], s[0:1], v64, s0, v[0:1]
	v_readlane_b32 s37, v254, 48
	v_readlane_b32 s2, v253, 36
	v_lshlrev_b32_e32 v2, 5, v106
	s_lshl_b32 s0, s37, 1
	s_mov_b32 s1, s2
	v_and_b32_e32 v4, 0x60, v2
	v_readlane_b32 s3, v253, 37
	v_lshl_add_u64 v[0:1], v[0:1], 0, s[0:1]
	v_lshlrev_b32_e32 v194, 1, v4
	v_lshl_add_u64 v[0:1], v[0:1], 0, v[194:195]
	s_mov_b64 s[2:3], 0x1820
	s_movk_i32 s4, 0x1000
	v_lshl_add_u64 v[2:3], v[0:1], 0, s[2:3]
	v_add_co_u32_e32 v0, vcc, s4, v0
	s_lshl_b32 s2, s37, 2
	s_nop 0
	v_addc_co_u32_e32 v1, vcc, 0, v1, vcc
	flat_load_dwordx4 v[52:55], v[2:3] offset:16
	flat_load_dwordx4 v[28:31], v[2:3] offset:32
	flat_load_dwordx4 v[66:69], v[0:1] offset:2080
	flat_load_dwordx4 v[8:11], v[2:3] offset:48
	v_readlane_b32 s3, v254, 49
	s_add_u32 s2, s3, s2
	v_readlane_b32 s3, v254, 46
	s_addc_u32 s3, s3, 0
	v_lshlrev_b32_e32 v12, 2, v4
	s_nop 2
	global_load_dwordx4 v[36:39], v12, s[2:3] offset:48
	global_load_dwordx4 v[44:47], v12, s[2:3] offset:32
	global_load_dwordx4 v[60:63], v12, s[2:3] offset:16
	global_load_dwordx4 v[116:119], v12, s[2:3]
	global_load_dwordx4 v[0:3], v12, s[2:3] offset:112
	global_load_dwordx4 v[4:7], v12, s[2:3] offset:96
	global_load_dwordx4 v[16:19], v12, s[2:3] offset:80
	global_load_dwordx4 v[24:27], v12, s[2:3] offset:64
	s_movk_i32 s2, 0x210
	v_lshl_add_u32 v13, v110, 7, 0
	v_lshlrev_b32_e32 v14, 2, v111
	v_mul_lo_u32 v15, v73, s2
	v_add3_u32 v13, v13, v14, v15
	v_add_u32_e32 v14, 0x9000, v13
	ds_write2_b32 v14, v74, v92 offset1:16
	ds_write2_b32 v14, v75, v93 offset0:132 offset1:148
	v_add_u32_e32 v14, 0x9400, v13
	ds_write2_b32 v14, v76, v88 offset0:8 offset1:24
	ds_write2_b32 v14, v77, v89 offset0:140 offset1:156
	v_add_u32_e32 v14, 0xb000, v13
	ds_write2_b32 v14, v82, v98 offset0:64 offset1:80
	ds_write2_b32 v14, v83, v99 offset0:196 offset1:212
	v_add_u32_e32 v14, 0xb400, v13
	ds_write2_b32 v14, v78, v94 offset0:72 offset1:88
	ds_write2_b32 v14, v79, v95 offset0:204 offset1:220
	v_add_u32_e32 v14, 0xd000, v13
	ds_write2_b32 v14, v86, v102 offset0:128 offset1:144
	v_add_u32_e32 v14, 0xd400, v13
	ds_write2_b32 v14, v87, v103 offset0:4 offset1:20
	ds_write2_b32 v14, v80, v96 offset0:136 offset1:152
	v_add_u32_e32 v14, 0xd800, v13
	ds_write2_b32 v14, v81, v97 offset0:12 offset1:28
	v_add_u32_e32 v14, 0xf000, v13
	ds_write2_b32 v14, v90, v104 offset0:192 offset1:208
	v_add_u32_e32 v14, 0xf400, v13
	v_add_u32_e32 v13, 0xf800, v13
	ds_write2_b32 v14, v91, v105 offset0:68 offset1:84
	ds_write2_b32 v14, v84, v100 offset0:200 offset1:216
	ds_write2_b32 v13, v85, v101 offset0:76 offset1:92
	v_mul_lo_u32 v13, v109, s2
	v_add3_u32 v65, 0, v13, v12
	s_waitcnt lgkmcnt(0)
	s_barrier
; #define LAS __attribute__((address_space(3)))
; __device__ __forceinline__ void unpack8(u32x4 w, float* f) { f[0] = bflo(w.x); f[1] = bfhi(w.x); f[2] = bflo(w.y); f[3] = bfhi(w.y); f[4] = bflo(w.z); f[5] = bfhi(w.z); f[6] = bflo(w.w); f[7] = bfhi(w.w); }
; __device__ __forceinline__ u32x4 pack8(const float* f) { u32x4 w; w.x = cvt_pk_bf16(f[0], f[1]); w.y = cvt_pk_bf16(f[2], f[3]); w.z = cvt_pk_bf16(f[4], f[5]); w.w = cvt_pk_bf16(f[6], f[7]); return w; }
; __device__ __forceinline__ void ret_out(const Bufs& B, const float* __restrict__ g_out, int item, LAS unsigned char* lds) {
;     ...
;     { float ssq = 0.f; f32x4 x4[8];
; #pragma unroll
;         for (int i = 0; i < 8; ++i) { x4[i] = *(const LAS f32x4*)(HT + erow * 132 + eqd * 32 + i * 4);
;             ssq += x4[i][0] * x4[i][0] + x4[i][1] * x4[i][1] + x4[i][2] * x4[i][2] + x4[i][3] * x4[i][3]; }
;         ssq += __shfl_xor(ssq, 1); ssq += __shfl_xor(ssq, 2);
;         const float rstd = rsqrtf(ssq * (1.f / 128.f) + EPS_);
;         bf16_t* yo = B.Y + (size_t)es * DM + 512 + h * 128 + eqd * 32;
; #pragma unroll
;         for (int i = 0; i < 4; ++i) { float o8[8]; unpack8(og4[i], o8); float r8[8];
; #pragma unroll
;             for (int k = 0; k < 8; ++k) { const float sl = o8[k] * __builtin_amdgcn_rcpf(1.f + __expf(-o8[k])); r8[k] = sl * x4[2 * i + (k >> 2)][k & 3] * rstd * gp4[2 * i + (k >> 2)][k & 3]; }
;             *(u32x4*)(yo + i * 8) = pack8(r8); } }
	ds_read_b128 v[70:73], v65 offset:36864
	ds_read_b128 v[74:77], v65 offset:36880
	ds_read_b128 v[56:59], v65 offset:36896
	ds_read_b128 v[48:51], v65 offset:36912
	ds_read_b128 v[40:43], v65 offset:36928
	ds_read_b128 v[32:35], v65 offset:36944
	s_waitcnt lgkmcnt(0)
	v_mov_b32_e32 v14, v71
	v_mov_b32_e32 v15, v75
	v_mov_b32_e32 v12, v70
	v_mov_b32_e32 v13, v74
	v_pk_mul_f32 v[14:15], v[14:15], v[14:15]
	v_mov_b32_e32 v84, v43
	v_pk_fma_f32 v[12:13], v[12:13], v[12:13], v[14:15]
	v_mov_b32_e32 v14, v72
	v_mov_b32_e32 v15, v76
	v_pk_fma_f32 v[12:13], v[14:15], v[14:15], v[12:13]
	v_mov_b32_e32 v14, v73
	v_mov_b32_e32 v15, v77
	v_pk_fma_f32 v[78:79], v[14:15], v[14:15], v[12:13]
	v_mov_b32_e32 v14, v57
	v_mov_b32_e32 v15, v49
	v_mov_b32_e32 v12, v56
	v_mov_b32_e32 v13, v48
	v_pk_mul_f32 v[14:15], v[14:15], v[14:15]
	v_mov_b32_e32 v85, v35
	v_pk_fma_f32 v[12:13], v[12:13], v[12:13], v[14:15]
	v_mov_b32_e32 v14, v58
	v_mov_b32_e32 v15, v50
	v_pk_fma_f32 v[12:13], v[14:15], v[14:15], v[12:13]
	v_mov_b32_e32 v14, v59
	v_mov_b32_e32 v15, v51
	v_pk_fma_f32 v[80:81], v[14:15], v[14:15], v[12:13]
	v_mov_b32_e32 v14, v41
	v_mov_b32_e32 v15, v33
	v_mov_b32_e32 v12, v40
	v_mov_b32_e32 v13, v32
	v_pk_mul_f32 v[14:15], v[14:15], v[14:15]
	s_mov_b32 s2, 0x800000
	v_pk_fma_f32 v[12:13], v[12:13], v[12:13], v[14:15]
	v_mov_b32_e32 v14, v42
	v_mov_b32_e32 v15, v34
	v_pk_fma_f32 v[82:83], v[14:15], v[14:15], v[12:13]
	ds_read_b128 v[20:23], v65 offset:36960
	ds_read_b128 v[12:15], v65 offset:36976
	v_add_f32_e32 v65, v78, v79
	v_pk_fma_f32 v[82:83], v[84:85], v[84:85], v[82:83]
	v_add_f32_e32 v65, v65, v80
	s_waitcnt lgkmcnt(0)
	v_mov_b32_e32 v86, v21
	v_mov_b32_e32 v87, v13
	v_mov_b32_e32 v84, v20
	v_mov_b32_e32 v85, v12
	v_pk_mul_f32 v[86:87], v[86:87], v[86:87]
	v_add_f32_e32 v65, v65, v81
	v_pk_fma_f32 v[84:85], v[84:85], v[84:85], v[86:87]
	v_mov_b32_e32 v86, v22
	v_mov_b32_e32 v87, v14
	v_pk_fma_f32 v[84:85], v[86:87], v[86:87], v[84:85]
	v_mov_b32_e32 v86, v23
	v_mov_b32_e32 v87, v15
	v_add_f32_e32 v65, v65, v82
	v_pk_fma_f32 v[84:85], v[86:87], v[86:87], v[84:85]
	v_add_f32_e32 v65, v65, v83
	v_add_f32_e32 v65, v65, v84
	v_add_f32_e32 v65, v65, v85
	ds_bpermute_b32 v78, v113, v65
	s_waitcnt vmcnt(0)
	v_lshlrev_b32_e32 v80, 16, v67
	v_and_b32_e32 v67, 0xffff0000, v67
	v_lshlrev_b32_e32 v82, 16, v68
	v_and_b32_e32 v68, 0xffff0000, v68
	s_waitcnt lgkmcnt(0)
	v_add_f32_e32 v65, v65, v78
	ds_bpermute_b32 v78, v114, v65
	v_lshlrev_b32_e32 v83, 16, v69
	v_and_b32_e32 v69, 0xffff0000, v69
	v_readlane_b32 s37, v254, 54
	s_waitcnt lgkmcnt(0)
	v_add_f32_e32 v65, v65, v78
	v_fmamk_f32 v65, v65, 0x3c000000, v242
	v_mul_f32_e32 v78, 0x4b800000, v65
	v_cmp_gt_f32_e32 vcc, s2, v65
	v_readlane_b32 s2, v254, 42
	v_readlane_b32 s3, v254, 43
	v_cndmask_b32_e32 v65, v65, v78, vcc
	v_rsq_f32_e32 v78, v65
	v_ashrrev_i32_e32 v65, 31, v64
	v_lshlrev_b64 v[64:65], 12, v[64:65]
	v_lshl_add_u64 v[64:65], s[2:3], 0, v[64:65]
	v_mul_f32_e32 v79, 0x45800000, v78
	v_cndmask_b32_e32 v78, v78, v79, vcc
	v_lshlrev_b32_e32 v79, 16, v66
	v_mul_f32_e32 v81, 0xbfb8aa3b, v79
	v_exp_f32_e32 v81, v81
	v_and_b32_e32 v66, 0xffff0000, v66
	v_mul_f32_e32 v84, 0xbfb8aa3b, v66
	v_exp_f32_e32 v84, v84
	v_add_f32_e32 v81, 1.0, v81
	v_rcp_f32_e32 v81, v81
	v_lshl_add_u64 v[64:65], v[64:65], 0, s[0:1]
	v_lshl_add_u64 v[64:65], v[64:65], 0, v[194:195]
	v_readlane_b32 s0, v252, 9
	v_mul_f32_e32 v79, v81, v79
	v_mul_f32_e32 v70, v79, v70
	v_add_f32_e32 v79, 1.0, v84
	v_rcp_f32_e32 v79, v79
	v_mul_f32_e32 v81, 0xbfb8aa3b, v80
	v_exp_f32_e32 v81, v81
	v_mul_f32_e32 v70, v70, v78
	v_mul_f32_e32 v66, v79, v66
	v_mul_f32_e32 v66, v66, v71
	v_add_f32_e32 v71, 1.0, v81
	v_rcp_f32_e32 v71, v71
	v_mul_f32_e32 v79, 0xbfb8aa3b, v67
	v_exp_f32_e32 v79, v79
	v_mul_f32_e32 v66, v66, v78
	v_mul_f32_e32 v71, v71, v80
	v_mul_f32_e32 v71, v71, v72
	v_add_f32_e32 v72, 1.0, v79
	v_rcp_f32_e32 v72, v72
	v_mul_f32_e32 v79, 0xbfb8aa3b, v82
	v_exp_f32_e32 v79, v79
	v_mul_f32_e32 v70, v116, v70
	v_mul_f32_e32 v67, v72, v67
	v_mul_f32_e32 v67, v67, v73
	v_mul_f32_e32 v73, 0xbfb8aa3b, v68
	v_add_f32_e32 v72, 1.0, v79
	v_exp_f32_e32 v73, v73
	v_rcp_f32_e32 v72, v72
	v_mul_f32_e32 v66, v117, v66
	v_mul_f32_e32 v71, v71, v78
	v_add_f32_e32 v73, 1.0, v73
	v_mul_f32_e32 v72, v72, v82
	v_rcp_f32_e32 v73, v73
	v_mul_f32_e32 v72, v72, v74
	v_mul_f32_e32 v74, 0xbfb8aa3b, v83
	v_exp_f32_e32 v74, v74
	v_mul_f32_e32 v72, v72, v78
	v_mul_f32_e32 v72, v60, v72
	v_mul_f32_e32 v60, v73, v68
	v_mul_f32_e32 v73, 0xbfb8aa3b, v69
	v_exp_f32_e32 v73, v73
	v_add_f32_e32 v68, 1.0, v74
	v_mul_f32_e32 v60, v60, v75
	v_rcp_f32_e32 v68, v68
	v_mul_f32_e32 v60, v60, v78
	v_mul_f32_e32 v74, v61, v60
	v_add_f32_e32 v61, 1.0, v73
	v_rcp_f32_e32 v61, v61
	v_mul_f32_e32 v60, v68, v83
	v_mul_f32_e32 v60, v60, v76
	v_mul_f32_e32 v60, v60, v78
	v_mul_f32_e32 v68, v62, v60
	v_mul_f32_e32 v60, v61, v69
	v_mul_f32_e32 v60, v60, v77
	v_mul_f32_e32 v60, v60, v78
	v_mul_f32_e32 v67, v67, v78
	v_mul_f32_e32 v63, v63, v60
	v_cvt_pk_bf16_f32 v60, v70, v66
	v_mul_f32_e32 v71, v118, v71
	v_mul_f32_e32 v67, v119, v67
	v_cvt_pk_bf16_f32 v61, v71, v67
	v_cvt_pk_bf16_f32 v62, v72, v74
	v_cvt_pk_bf16_f32 v63, v68, v63
	flat_store_dwordx4 v[64:65], v[60:63] offset:1024
	v_lshlrev_b32_e32 v66, 16, v55
	v_and_b32_e32 v55, 0xffff0000, v55
	v_lshlrev_b32_e32 v60, 16, v52
	v_mul_f32_e32 v62, 0xbfb8aa3b, v60
	v_exp_f32_e32 v62, v62
	v_and_b32_e32 v52, 0xffff0000, v52
	v_mul_f32_e32 v67, 0xbfb8aa3b, v52
	v_exp_f32_e32 v67, v67
	v_add_f32_e32 v62, 1.0, v62
	v_rcp_f32_e32 v62, v62
	v_lshlrev_b32_e32 v61, 16, v53
	v_and_b32_e32 v53, 0xffff0000, v53
	v_lshlrev_b32_e32 v63, 16, v54
; __device__ __forceinline__ void unpack8(u32x4 w, float* f) { f[0] = bflo(w.x); f[1] = bfhi(w.x); f[2] = bflo(w.y); f[3] = bfhi(w.y); f[4] = bflo(w.z); f[5] = bfhi(w.z); f[6] = bflo(w.w); f[7] = bfhi(w.w); }
; __device__ __forceinline__ u32x4 pack8(const float* f) { u32x4 w; w.x = cvt_pk_bf16(f[0], f[1]); w.y = cvt_pk_bf16(f[2], f[3]); w.z = cvt_pk_bf16(f[4], f[5]); w.w = cvt_pk_bf16(f[6], f[7]); return w; }
; __device__ __forceinline__ void ret_out(const Bufs& B, const float* __restrict__ g_out, int item, LAS unsigned char* lds) {
;     ...
;         for (int i = 0; i < 4; ++i) { float o8[8]; unpack8(og4[i], o8); float r8[8];
; #pragma unroll
;             for (int k = 0; k < 8; ++k) { const float sl = o8[k] * __builtin_amdgcn_rcpf(1.f + __expf(-o8[k])); r8[k] = sl * x4[2 * i + (k >> 2)][k & 3] * rstd * gp4[2 * i + (k >> 2)][k & 3]; }
;             *(u32x4*)(yo + i * 8) = pack8(r8); } }
;     __syncthreads();
; __global__ void __launch_bounds__(512) mega_fwd(Params p) {
;     ...
;             for (int it = bx; it < 256; it += G) ret_out(B, p.g_ret_out + l * 512, it, lds);
;             for (int it = bx; it < 256; it += G) { const int h = it & 7, qb = it >> 3;
	v_mul_f32_e32 v60, v62, v60
	v_mul_f32_e32 v56, v60, v56
	v_add_f32_e32 v60, 1.0, v67
	v_rcp_f32_e32 v60, v60
	v_mul_f32_e32 v56, v56, v78
	v_mul_f32_e32 v44, v44, v56
	v_mul_f32_e32 v56, 0xbfb8aa3b, v61
	v_exp_f32_e32 v56, v56
	v_mul_f32_e32 v52, v60, v52
	v_mul_f32_e32 v52, v52, v57
	v_mul_f32_e32 v52, v52, v78
	v_mul_f32_e32 v45, v45, v52
	v_mul_f32_e32 v52, 0xbfb8aa3b, v53
	v_add_f32_e32 v56, 1.0, v56
	v_exp_f32_e32 v52, v52
	v_rcp_f32_e32 v56, v56
	v_and_b32_e32 v54, 0xffff0000, v54
	s_add_i32 s0, s37, s0
	v_add_f32_e32 v52, 1.0, v52
	v_mul_f32_e32 v56, v56, v61
	v_rcp_f32_e32 v52, v52
	v_mul_f32_e32 v56, v56, v58
	v_mul_f32_e32 v56, v56, v78
	v_mul_f32_e32 v46, v46, v56
	v_mul_f32_e32 v56, 0xbfb8aa3b, v63
	v_exp_f32_e32 v56, v56
	v_mul_f32_e32 v52, v52, v53
	v_mul_f32_e32 v52, v52, v59
	v_mul_f32_e32 v52, v52, v78
	v_mul_f32_e32 v47, v47, v52
	v_mul_f32_e32 v52, 0xbfb8aa3b, v54
	v_add_f32_e32 v53, 1.0, v56
	v_exp_f32_e32 v52, v52
	v_rcp_f32_e32 v53, v53
	s_cmpk_lt_i32 s0, 0x100
	v_readlane_b32 s1, v252, 10
	v_add_f32_e32 v52, 1.0, v52
	v_mul_f32_e32 v53, v53, v63
	v_rcp_f32_e32 v52, v52
	v_mul_f32_e32 v48, v53, v48
	v_mul_f32_e32 v53, 0xbfb8aa3b, v66
	v_exp_f32_e32 v53, v53
	v_mul_f32_e32 v48, v48, v78
	v_mul_f32_e32 v48, v36, v48
	v_mul_f32_e32 v36, v52, v54
	v_mul_f32_e32 v52, 0xbfb8aa3b, v55
	v_exp_f32_e32 v52, v52
	v_mul_f32_e32 v36, v36, v49
	v_add_f32_e32 v49, 1.0, v53
	v_rcp_f32_e32 v49, v49
	v_mul_f32_e32 v36, v36, v78
	v_mul_f32_e32 v53, v37, v36
	v_add_f32_e32 v37, 1.0, v52
	v_rcp_f32_e32 v37, v37
	v_mul_f32_e32 v36, v49, v66
	v_mul_f32_e32 v36, v36, v50
	v_mul_f32_e32 v36, v36, v78
	v_mul_f32_e32 v49, v38, v36
	v_mul_f32_e32 v36, v37, v55
	v_mul_f32_e32 v36, v36, v51
	v_mul_f32_e32 v36, v36, v78
	v_mul_f32_e32 v39, v39, v36
	v_cvt_pk_bf16_f32 v36, v44, v45
	v_cvt_pk_bf16_f32 v37, v46, v47
	v_cvt_pk_bf16_f32 v38, v48, v53
	v_cvt_pk_bf16_f32 v39, v49, v39
	flat_store_dwordx4 v[64:65], v[36:39] offset:1040
	v_lshlrev_b32_e32 v44, 16, v31
	v_and_b32_e32 v31, 0xffff0000, v31
	v_lshlrev_b32_e32 v36, 16, v28
	v_mul_f32_e32 v38, 0xbfb8aa3b, v36
	v_exp_f32_e32 v38, v38
	v_and_b32_e32 v28, 0xffff0000, v28
	v_mul_f32_e32 v45, 0xbfb8aa3b, v28
	v_exp_f32_e32 v45, v45
	v_add_f32_e32 v38, 1.0, v38
	v_rcp_f32_e32 v38, v38
	v_lshlrev_b32_e32 v37, 16, v29
	v_and_b32_e32 v29, 0xffff0000, v29
	v_lshlrev_b32_e32 v39, 16, v30
	v_mul_f32_e32 v36, v38, v36
	v_add_f32_e32 v38, 1.0, v45
	v_rcp_f32_e32 v38, v38
	v_mul_f32_e32 v36, v36, v40
	v_mul_f32_e32 v36, v36, v78
	v_mul_f32_e32 v24, v24, v36
	v_mul_f32_e32 v36, 0xbfb8aa3b, v37
	v_exp_f32_e32 v36, v36
	v_mul_f32_e32 v28, v38, v28
	v_mul_f32_e32 v28, v28, v41
	v_mul_f32_e32 v28, v28, v78
	v_mul_f32_e32 v25, v25, v28
	v_mul_f32_e32 v28, 0xbfb8aa3b, v29
	v_add_f32_e32 v36, 1.0, v36
	v_exp_f32_e32 v28, v28
	v_rcp_f32_e32 v36, v36
	v_and_b32_e32 v30, 0xffff0000, v30
	v_add_f32_e32 v28, 1.0, v28
	v_mul_f32_e32 v36, v36, v37
	v_rcp_f32_e32 v28, v28
	v_mul_f32_e32 v36, v36, v42
	v_mul_f32_e32 v36, v36, v78
	v_mul_f32_e32 v26, v26, v36
	v_mul_f32_e32 v36, 0xbfb8aa3b, v39
	v_exp_f32_e32 v36, v36
	v_mul_f32_e32 v28, v28, v29
	v_mul_f32_e32 v28, v28, v43
	v_mul_f32_e32 v28, v28, v78
	v_mul_f32_e32 v27, v27, v28
	v_mul_f32_e32 v28, 0xbfb8aa3b, v30
	v_add_f32_e32 v29, 1.0, v36
	v_exp_f32_e32 v28, v28
	v_rcp_f32_e32 v29, v29
	v_add_f32_e32 v28, 1.0, v28
	v_mul_f32_e32 v29, v29, v39
	v_rcp_f32_e32 v28, v28
	v_mul_f32_e32 v29, v29, v32
	v_mul_f32_e32 v32, 0xbfb8aa3b, v44
	v_exp_f32_e32 v32, v32
	v_mul_f32_e32 v29, v29, v78
	v_mul_f32_e32 v29, v16, v29
	v_mul_f32_e32 v16, v28, v30
	v_mul_f32_e32 v30, 0xbfb8aa3b, v31
	v_exp_f32_e32 v30, v30
	v_add_f32_e32 v28, 1.0, v32
	v_mul_f32_e32 v16, v16, v33
	v_rcp_f32_e32 v28, v28
	v_mul_f32_e32 v16, v16, v78
	v_mul_f32_e32 v32, v17, v16
	v_add_f32_e32 v17, 1.0, v30
	v_rcp_f32_e32 v17, v17
	v_mul_f32_e32 v16, v28, v44
	v_mul_f32_e32 v16, v16, v34
	v_mul_f32_e32 v16, v16, v78
	v_mul_f32_e32 v28, v18, v16
	v_mul_f32_e32 v16, v17, v31
	v_mul_f32_e32 v16, v16, v35
	v_mul_f32_e32 v16, v16, v78
	v_mul_f32_e32 v19, v19, v16
	v_cvt_pk_bf16_f32 v16, v24, v25
	v_cvt_pk_bf16_f32 v17, v26, v27
	v_cvt_pk_bf16_f32 v18, v29, v32
	v_cvt_pk_bf16_f32 v19, v28, v19
	flat_store_dwordx4 v[64:65], v[16:19] offset:1056
	v_lshlrev_b32_e32 v24, 16, v11
	v_and_b32_e32 v11, 0xffff0000, v11
	v_lshlrev_b32_e32 v16, 16, v8
	v_mul_f32_e32 v18, 0xbfb8aa3b, v16
	v_exp_f32_e32 v18, v18
	v_and_b32_e32 v8, 0xffff0000, v8
	v_mul_f32_e32 v25, 0xbfb8aa3b, v8
	v_exp_f32_e32 v25, v25
	v_add_f32_e32 v18, 1.0, v18
	v_rcp_f32_e32 v18, v18
	v_lshlrev_b32_e32 v17, 16, v9
	v_and_b32_e32 v9, 0xffff0000, v9
	v_lshlrev_b32_e32 v19, 16, v10
	v_mul_f32_e32 v16, v18, v16
	v_add_f32_e32 v18, 1.0, v25
	v_rcp_f32_e32 v18, v18
	v_mul_f32_e32 v16, v16, v20
	v_mul_f32_e32 v16, v16, v78
	v_mul_f32_e32 v4, v4, v16
	v_mul_f32_e32 v16, 0xbfb8aa3b, v17
	v_exp_f32_e32 v16, v16
	v_mul_f32_e32 v8, v18, v8
	v_mul_f32_e32 v8, v8, v21
	v_mul_f32_e32 v8, v8, v78
	v_mul_f32_e32 v5, v5, v8
	v_mul_f32_e32 v8, 0xbfb8aa3b, v9
	v_add_f32_e32 v16, 1.0, v16
	v_exp_f32_e32 v8, v8
	v_rcp_f32_e32 v16, v16
	v_and_b32_e32 v10, 0xffff0000, v10
	v_add_f32_e32 v8, 1.0, v8
	v_mul_f32_e32 v16, v16, v17
	v_rcp_f32_e32 v8, v8
	v_mul_f32_e32 v16, v16, v22
	v_mul_f32_e32 v16, v16, v78
	v_mul_f32_e32 v6, v6, v16
	v_mul_f32_e32 v16, 0xbfb8aa3b, v19
	v_exp_f32_e32 v16, v16
	v_mul_f32_e32 v8, v8, v9
	v_mul_f32_e32 v8, v8, v23
	v_mul_f32_e32 v8, v8, v78
	v_mul_f32_e32 v7, v7, v8
	v_mul_f32_e32 v8, 0xbfb8aa3b, v10
	v_add_f32_e32 v9, 1.0, v16
	v_exp_f32_e32 v8, v8
	v_rcp_f32_e32 v9, v9
	v_add_f32_e32 v8, 1.0, v8
	v_mul_f32_e32 v9, v9, v19
	v_rcp_f32_e32 v8, v8
	v_mul_f32_e32 v9, v9, v12
	v_mul_f32_e32 v12, 0xbfb8aa3b, v24
	v_exp_f32_e32 v12, v12
	v_mul_f32_e32 v9, v9, v78
	v_mul_f32_e32 v9, v0, v9
	v_mul_f32_e32 v0, v8, v10
	v_mul_f32_e32 v10, 0xbfb8aa3b, v11
	v_exp_f32_e32 v10, v10
	v_add_f32_e32 v8, 1.0, v12
	v_mul_f32_e32 v0, v0, v13
	v_rcp_f32_e32 v8, v8
	v_mul_f32_e32 v0, v0, v78
	v_mul_f32_e32 v12, v1, v0
	v_add_f32_e32 v1, 1.0, v10
	v_rcp_f32_e32 v1, v1
	v_mul_f32_e32 v0, v8, v24
	v_mul_f32_e32 v0, v0, v14
	v_mul_f32_e32 v0, v0, v78
	v_mul_f32_e32 v8, v2, v0
	v_mul_f32_e32 v0, v1, v11
	v_mul_f32_e32 v0, v0, v15
	v_mul_f32_e32 v0, v0, v78
	v_mul_f32_e32 v3, v3, v0
	v_cvt_pk_bf16_f32 v0, v4, v5
	v_cvt_pk_bf16_f32 v1, v6, v7
	v_cvt_pk_bf16_f32 v2, v9, v12
	v_cvt_pk_bf16_f32 v3, v8, v3
	flat_store_dwordx4 v[64:65], v[0:3] offset:1072
	s_waitcnt lgkmcnt(0)
	s_barrier
	s_cbranch_scc1 .LBB0_245
	v_readlane_b32 s0, v255, 62
	s_cmp_eq_u32 s0, 2
	s_cbranch_scc1 .LBB0_297
	v_readlane_b32 s0, v254, 4
	v_readlane_b32 s24, v254, 3
	s_mov_b32 s25, s0
	v_readlane_b32 s1, v254, 5
	s_branch .LBB0_260

; __global__ void __launch_bounds__(512) mega_fwd(Params p) {
;     ...
;             for (int it = bx; it < 256; it += G) { const int h = it & 7, qb = it >> 3;
;                 att::attn_body((const unsigned char*)B.Q + ((size_t)h * S_ + qb * 256) * 192, (const unsigned char*)B.K + (size_t)h * S_ * 192, (const unsigned char*)B.V + (size_t)h * 128 * S_,
;                                B.Y + (size_t)(qb * 256) * DM + 1024 + h * 128, S_, (char*)lds_raw); }
.Lsub4_after_attn:
	v_readlane_b32 s0, v255, 62
	s_cmp_eq_u32 s0, 1
	s_cbranch_scc0 .LBB0_297
	s_mov_b32 s0, 2
	v_writelane_b32 v255, s0, 62
	s_branch .Lsub4_mixers
.Lsub4_attn_first:
	v_readlane_b32 s0, v254, 4
	v_readlane_b32 s24, v254, 3
	s_mov_b32 s25, s0
	v_readlane_b32 s1, v254, 5
	s_branch .LBB0_260
